# UT chunk operand stored in 16-row blocks [col piece][row]: coalesced producer stores and 512 B contiguous consumer loads
# baseline (speedup 1.0000x reference)
; __device__ __forceinline__ int opaque_tid() { int t = threadIdx.x; asm volatile("" : "+v"(t)); return t; }
; __device__ __forceinline__ int bid() { int b = blockIdx.x; asm volatile("" : "+s"(b)); return b; }
; __device__ __forceinline__ int gdim() { int g = gridDim.x; asm volatile("" : "+s"(g)); return g; }
; DI int xcd_group_item(int blk, int G) { if (G != 256) return blk; const int x = blk & 7, k = blk >> 3; return ((x + 8 * (k >> 2)) << 2) + (k & 3); }
; DI void phase_dn_chunkrec(PrmC p, unsigned char* smem) {
;     ...
;     const int tid = opaque_tid(), lane = tid & 63, wave = tid >> 6, r16 = lane & 15, q4 = lane >> 4, rt = wave >> 1, ct = wave & 1;
;     for (int item0 = bid(); item0 < 256; item0 += gdim()) {
;         const int item = xcd_group_item(item0, gdim());
;         const int sl = item & 3, dir = (item >> 2) & 1, h = (item >> 3) & 3, b = item >> 5, bh = b * 4 + h;
;         f32x4 Sacc[2];
;         Sacc[0] = (f32x4){0.f, 0.f, 0.f, 0.f}; Sacc[1] = Sacc[0];
;         __syncthreads();
;         for (int i = tid; i < 32 * DS_PITCH / 16; i += NTHR) *(uint4*)(smem + D_ST + i * 16) = make_uint4(0, 0, 0, 0);
;         uint4 wf0, wf1, wf2, wf3, qf0, qf1, qf2, qf3, qk0, qk1, kd00, kd01, kd10, kd11; uint2 uf;
;         uint4 nwf0, nwf1, nwf2, nwf3, nqf0, nqf1, nqf2, nqf3, nqk0, nqk1, nkd00, nkd01, nkd10, nkd11; uint2 nuf;
;     ...
;         if (tid < 36) ((float*)(smem + D_EG))[tid] = DEG[(size_t)dir * 1152 + bh * 36 + DC_CIDX(tid)];
.LBB0_286:
	s_andn2_b64 vcc, exec, s[6:7]
	s_cbranch_vccnz .LBB0_321
	s_waitcnt vmcnt(0)
	v_mov_b32_e32 v122, v195
	v_readlane_b32 s4, v254, 0
	s_cmpk_gt_i32 s4, 0xff
	s_cbranch_scc1 .LBB0_321
	v_bfe_u32 v11, v122, 4, 2
	v_lshlrev_b32_e32 v124, 4, v11
	v_mov_b32_e32 v125, v1
	v_lshl_add_u64 v[6:7], s[66:67], 0, v[124:125]
	s_mov_b64 s[12:13], 0x1f86a000
	v_lshl_add_u64 v[126:127], v[6:7], 0, s[12:13]
	s_mov_b64 s[12:13], 0x21c6a000
	v_ashrrev_i32_e32 v10, 7, v122
	v_lshl_add_u64 v[128:129], v[6:7], 0, s[12:13]
	s_mov_b64 s[12:13], 0x2646a000
	v_lshlrev_b32_e32 v2, 4, v10
	v_lshl_add_u64 v[130:131], v[6:7], 0, s[12:13]
	s_mov_b64 s[12:13], 0x2406a000
	v_ashrrev_i32_e32 v3, 31, v2
	v_lshl_add_u64 v[134:135], v[6:7], 0, s[12:13]
	v_lshrrev_b32_e32 v6, 2, v122
	v_and_b32_e32 v8, 15, v122
	v_lshlrev_b32_e32 v166, 11, v10
	v_lshl_add_u32 v166, v11, 7, v166
	v_lshlrev_b32_e32 v167, 3, v11
	v_sub_u32_e32 v166, v166, v167
	v_lshl_add_u32 v166, v8, 3, v166
	v_mov_b32_e32 v167, 0
	v_lshlrev_b32_e32 v168, 11, v10
	v_lshl_add_u32 v168, v11, 8, v168
	v_lshlrev_b32_e32 v169, 4, v11
	v_sub_u32_e32 v168, v168, v169
	v_lshl_add_u32 v168, v8, 4, v168
	v_mov_b32_e32 v169, 0
	v_lshlrev_b32_e32 v170, 9, v10
	v_lshl_add_u32 v170, v8, 4, v170
	v_lshrrev_b32_e32 v171, 1, v11
	v_lshl_add_u32 v170, v171, 8, v170
	v_and_b32_e32 v171, 1, v11
	v_lshl_add_u32 v170, v171, 3, v170
	v_mov_b32_e32 v171, 0
	v_mov_b32_e32 v5, v3
	v_lshlrev_b32_e32 v0, 3, v11
	v_and_b32_e32 v12, 16, v6
	v_lshl_add_u64 v[6:7], v[2:3], 1, s[66:67]
	v_lshlrev_b32_e32 v3, 2, v11
	v_or_b32_e32 v4, v2, v8
	v_lshlrev_b32_e32 v10, 5, v10
	v_lshl_add_u64 v[6:7], v[6:7], 0, v[0:1]
	s_mov_b64 s[12:13], 0x2766a000
	v_or_b32_e32 v2, v3, v2
	v_lshl_add_u32 v9, v8, 2, 0
	v_or_b32_e32 v132, v10, v8
	v_or_b32_e32 v125, v12, v8
	v_lshl_add_u64 v[136:137], s[66:67], 0, v[170:171]
	v_lshl_add_u64 v[136:137], v[136:137], 0, s[12:13]
	v_lshlrev_b32_e32 v7, 1, v2
	v_lshlrev_b32_e32 v8, 2, v12
	v_lshlrev_b32_e32 v2, 7, v2
	v_add3_u32 v155, v9, v8, v2
	v_max_i32_e32 v2, 32, v122
	v_sub_u32_e32 v2, v2, v122
	s_movk_i32 s12, 0x110
	v_add_u32_e32 v2, 0x1ff, v2
	s_add_u32 s5, s66, 0x2be6a000
	v_mad_u32_u24 v6, v125, s12, 0
	v_lshlrev_b32_e32 v0, 7, v125
	v_lshlrev_b64 v[138:139], 7, v[4:5]
	v_lshrrev_b32_e32 v4, 9, v2
	s_addc_u32 s25, s67, 0
	v_sub_u32_e32 v153, v6, v0
	v_lshlrev_b32_e32 v0, 3, v122
	v_add_u32_e32 v4, 1, v4
	s_add_u32 s27, s66, 0x1554a000
	s_movk_i32 s6, 0x220
	v_or_b32_e32 v3, v3, v10
	v_and_b32_e32 v0, 24, v0
	s_movk_i32 s12, 0x1ff
	v_and_b32_e32 v156, 0xfffffe, v4
	s_addc_u32 s28, s67, 0
	v_cmp_gt_i32_e64 s[6:7], s6, v122
	v_cmp_lt_i32_e64 s[8:9], 35, v122
	v_cmp_gt_i32_e64 s[10:11], 4, v122
	v_sub_u32_e32 v145, 39, v122
	v_sub_u32_e32 v150, 3, v122
	v_lshl_add_u32 v151, v122, 2, 0
	v_ashrrev_i32_e32 v133, 31, v10
	v_add_u32_e32 v152, v6, v124
	v_lshl_add_u32 v154, v0, 2, 0
	v_cmp_lt_u32_e64 s[12:13], s12, v2
	v_lshl_add_u32 v157, v156, 9, v122
	v_add_u32_e32 v123, 0x200, v122
	v_cmp_ne_u32_e64 s[14:15], v4, v156
	v_lshl_add_u32 v158, v3, 1, v6
	v_lshlrev_b32_e32 v0, 1, v0
	v_add_u32_e32 v159, v153, v7

; DI void phase_dn_chunkrec(PrmC p, unsigned char* smem) {
;     ...
;         if (tid < 36) ((float*)(smem + D_EG))[tid] = DEG[(size_t)dir * 1152 + bh * 36 + DC_CIDX(tid)];
;         DC_LOAD(0, );
;         __syncthreads();
.LBB0_301:
	s_or_b64 exec, exec, s[20:21]
	s_cmp_eq_u32 s31, 0
	s_cselect_b64 s[16:17], -1, 0
	s_and_b64 s[18:19], s[16:17], exec
	v_lshl_add_u64 v[142:143], v[60:61], 0, v[58:59]
	s_cselect_b32 s18, 0, 3
	v_or_b32_e32 v58, s18, v142
	v_mov_b32_e32 v59, v143
	v_lshlrev_b64 v[60:61], 13, v[58:59]
	v_lshl_add_u64 v[62:63], v[60:61], 0, v[166:167]
	v_lshl_add_u64 v[60:61], v[60:61], 0, v[168:169]
	v_lshlrev_b64 v[62:63], 1, v[62:63]
	v_lshl_add_u64 v[2:3], v[134:135], 0, v[62:63]
	v_lshl_add_u64 v[64:65], v[126:127], 0, v[62:63]
	v_lshl_add_u64 v[62:63], v[128:129], 0, v[62:63]
	global_load_dwordx4 v[114:117], v[64:65], off
	global_load_dwordx4 v[106:109], v[64:65], off offset:1024
	global_load_dwordx4 v[110:113], v[64:65], off offset:2048
	global_load_dwordx4 v[98:101], v[64:65], off offset:3072
	global_load_dwordx4 v[118:121], v[62:63], off
	global_load_dwordx4 v[102:105], v[62:63], off offset:1024
	global_load_dwordx4 v[94:97], v[62:63], off offset:2048
	global_load_dwordx4 v[90:93], v[62:63], off offset:3072
	v_lshl_add_u64 v[60:61], v[130:131], 0, v[60:61]
	v_lshlrev_b64 v[58:59], 7, v[58:59]
	s_lshl_b32 s18, s37, 5
	global_load_dwordx4 v[86:89], v[60:61], off
	global_load_dwordx4 v[82:85], v[60:61], off offset:1024
	v_lshl_add_u64 v[60:61], v[58:59], 0, v[132:133]
	s_and_b32 s18, s18, 0x60
	v_lshlrev_b64 v[60:61], 7, v[60:61]
	v_and_b32_e32 v144, 16, v125
	v_or_b32_e32 v144, s18, v144
	v_lshl_add_u64 v[60:61], v[134:135], 0, v[60:61]
	v_or_b32_e32 v58, v58, v144
	global_load_dwordx4 v[70:73], v[2:3], off
	global_load_dwordx4 v[78:81], v[2:3], off offset:1024
	global_load_dwordx4 v[74:77], v[2:3], off offset:2048
	global_load_dwordx4 v[66:69], v[2:3], off offset:3072
	v_lshlrev_b64 v[58:59], 7, v[58:59]
	v_lshl_add_u64 v[58:59], v[136:137], 0, v[58:59]
	global_load_dwordx2 v[148:149], v[58:59], off
	s_lshl_b32 s18, s18, 1
	s_add_u32 s20, s27, s18
	s_addc_u32 s21, s28, 0
	s_lshl_b32 s29, s29, 8
	s_add_u32 s20, s20, s29
	s_addc_u32 s21, s21, 0
	s_lshl_b32 s37, s30, 8
	v_mov_b32_e32 v58, 0
	s_mov_b32 s39, 0
	s_mul_i32 s18, s31, 0x4800
	s_mov_b32 s19, s36
	v_lshl_add_u64 v[146:147], s[20:21], 0, v[0:1]
	s_lshl_b32 s29, s30, 11
	s_addk_i32 s37, 0x4000
	v_mov_b32_e32 v59, v58
	v_mov_b32_e32 v60, v58
	v_mov_b32_e32 v61, v58
	v_mov_b32_e32 v62, v58
	v_mov_b32_e32 v63, v58
	v_mov_b32_e32 v64, v58
	v_mov_b32_e32 v65, v58
	s_waitcnt lgkmcnt(0)
	s_barrier
	s_add_i32 s38, s39, 1
	s_cmp_eq_u32 s39, 35
	s_cbranch_scc1 .LBB0_308
	s_branch .LBB0_303

; DI uint4 pack8(const float* f) { uint4 o; o.x = pk2(f[0], f[1]); o.y = pk2(f[2], f[3]); o.z = pk2(f[4], f[5]); o.w = pk2(f[6], f[7]); return o; }
; template <int D> DI void dn_out(float (&x)[64], lf_t Kl, lf_t Ql, lf_t Gn, bf16_t* DW, bf16_t* DQE, bf16_t* DKT, bf16_t* DUT, float* DEG, int item, int t) {
;     ...
;             if (t < 128) { bf16_t* uo = DUT + (((size_t)D * 1152 + item) * 128 + t) * 64;
; #pragma unroll
;                 for (int g8 = 0; g8 < 8; ++g8) *(uint4*)(uo + 8 * g8) = pack8(x + 8 * g8);
.LBB0_657:
	s_or_saveexec_b64 s[44:45], s[44:45]
	v_mov_b64_e32 v[8:9], s[42:43]
	s_xor_b64 exec, exec, s[44:45]
	s_cbranch_execz .LBB0_659
	s_lshl_b64 s[20:21], s[20:21], 14
	v_ashrrev_i32_e32 v5, 31, v4
	s_add_u32 s28, s94, s20
	s_addc_u32 s29, s96, s21
	v_and_b32_e32 v6, 15, v4
	v_lshrrev_b32_e32 v7, 4, v4
	v_lshlrev_b32_e32 v6, 4, v6
	v_lshl_add_u32 v6, v7, 11, v6
	v_mov_b32_e32 v7, 0
	v_lshl_add_u64 v[12:13], s[28:29], 0, v[6:7]
	v_and_b32_sdwa v6, v70, v242 dst_sel:DWORD dst_unused:UNUSED_PAD src0_sel:WORD_1 src1_sel:DWORD
	v_and_b32_sdwa v7, v73, v242 dst_sel:DWORD dst_unused:UNUSED_PAD src0_sel:WORD_1 src1_sel:DWORD
	v_and_b32_sdwa v0, v72, v242 dst_sel:DWORD dst_unused:UNUSED_PAD src0_sel:WORD_1 src1_sel:DWORD
	v_and_b32_sdwa v5, v2, v242 dst_sel:DWORD dst_unused:UNUSED_PAD src0_sel:WORD_1 src1_sel:DWORD
	v_add3_u32 v6, v70, v6, s71
	v_add3_u32 v7, v73, v7, s71
	v_add3_u32 v5, v2, v5, s71
	v_add3_u32 v0, v72, v0, s71
	v_and_b32_e32 v6, 0xffff0000, v6
	v_and_b32_e32 v8, 0xffff0000, v7
	v_or_b32_sdwa v7, v6, v0 dst_sel:DWORD dst_unused:UNUSED_PAD src0_sel:DWORD src1_sel:WORD_1
	v_or_b32_sdwa v6, v8, v5 dst_sel:DWORD dst_unused:UNUSED_PAD src0_sel:DWORD src1_sel:WORD_1
	v_and_b32_sdwa v8, v56, v242 dst_sel:DWORD dst_unused:UNUSED_PAD src0_sel:WORD_1 src1_sel:DWORD
	v_and_b32_sdwa v9, v67, v242 dst_sel:DWORD dst_unused:UNUSED_PAD src0_sel:WORD_1 src1_sel:DWORD
	v_and_b32_sdwa v0, v66, v242 dst_sel:DWORD dst_unused:UNUSED_PAD src0_sel:WORD_1 src1_sel:DWORD
	v_and_b32_sdwa v5, v71, v242 dst_sel:DWORD dst_unused:UNUSED_PAD src0_sel:WORD_1 src1_sel:DWORD
	v_add3_u32 v8, v56, v8, s71
	v_add3_u32 v9, v67, v9, s71
	v_add3_u32 v5, v71, v5, s71
	v_add3_u32 v0, v66, v0, s71
	v_and_b32_e32 v8, 0xffff0000, v8
	v_and_b32_e32 v10, 0xffff0000, v9
	v_or_b32_sdwa v9, v8, v0 dst_sel:DWORD dst_unused:UNUSED_PAD src0_sel:DWORD src1_sel:WORD_1
	v_or_b32_sdwa v8, v10, v5 dst_sel:DWORD dst_unused:UNUSED_PAD src0_sel:DWORD src1_sel:WORD_1
	global_store_dwordx4 v[12:13], v[6:9], off
	v_and_b32_sdwa v0, v51, v242 dst_sel:DWORD dst_unused:UNUSED_PAD src0_sel:WORD_1 src1_sel:DWORD
	v_and_b32_sdwa v5, v62, v242 dst_sel:DWORD dst_unused:UNUSED_PAD src0_sel:WORD_1 src1_sel:DWORD
	v_and_b32_sdwa v6, v3, v242 dst_sel:DWORD dst_unused:UNUSED_PAD src0_sel:WORD_1 src1_sel:DWORD
	v_and_b32_sdwa v7, v57, v242 dst_sel:DWORD dst_unused:UNUSED_PAD src0_sel:WORD_1 src1_sel:DWORD
	v_add3_u32 v6, v3, v6, s71
	v_add3_u32 v7, v57, v7, s71
	v_add3_u32 v5, v62, v5, s71
	v_add3_u32 v0, v51, v0, s71
	v_and_b32_e32 v6, 0xffff0000, v6
	v_and_b32_e32 v8, 0xffff0000, v7
	v_or_b32_sdwa v7, v6, v0 dst_sel:DWORD dst_unused:UNUSED_PAD src0_sel:DWORD src1_sel:WORD_1
	v_or_b32_sdwa v6, v8, v5 dst_sel:DWORD dst_unused:UNUSED_PAD src0_sel:DWORD src1_sel:WORD_1
	v_and_b32_sdwa v8, v50, v242 dst_sel:DWORD dst_unused:UNUSED_PAD src0_sel:WORD_1 src1_sel:DWORD
	v_and_b32_sdwa v9, v59, v242 dst_sel:DWORD dst_unused:UNUSED_PAD src0_sel:WORD_1 src1_sel:DWORD
	v_and_b32_sdwa v0, v58, v242 dst_sel:DWORD dst_unused:UNUSED_PAD src0_sel:WORD_1 src1_sel:DWORD
	v_and_b32_sdwa v5, v60, v242 dst_sel:DWORD dst_unused:UNUSED_PAD src0_sel:WORD_1 src1_sel:DWORD
	v_add3_u32 v8, v50, v8, s71
	v_add3_u32 v9, v59, v9, s71
	v_add3_u32 v5, v60, v5, s71
	v_add3_u32 v0, v58, v0, s71
	v_and_b32_e32 v8, 0xffff0000, v8
	v_and_b32_e32 v10, 0xffff0000, v9
	v_or_b32_sdwa v9, v8, v0 dst_sel:DWORD dst_unused:UNUSED_PAD src0_sel:DWORD src1_sel:WORD_1
	v_or_b32_sdwa v8, v10, v5 dst_sel:DWORD dst_unused:UNUSED_PAD src0_sel:DWORD src1_sel:WORD_1
	global_store_dwordx4 v[12:13], v[6:9], off offset:256
	v_and_b32_sdwa v0, v53, v242 dst_sel:DWORD dst_unused:UNUSED_PAD src0_sel:WORD_1 src1_sel:DWORD
	v_and_b32_sdwa v5, v55, v242 dst_sel:DWORD dst_unused:UNUSED_PAD src0_sel:WORD_1 src1_sel:DWORD
	v_and_b32_sdwa v6, v52, v242 dst_sel:DWORD dst_unused:UNUSED_PAD src0_sel:WORD_1 src1_sel:DWORD
	v_and_b32_sdwa v7, v54, v242 dst_sel:DWORD dst_unused:UNUSED_PAD src0_sel:WORD_1 src1_sel:DWORD
	v_add3_u32 v6, v52, v6, s71
	v_add3_u32 v7, v54, v7, s71
	v_add3_u32 v5, v55, v5, s71
	v_add3_u32 v0, v53, v0, s71
	v_and_b32_e32 v6, 0xffff0000, v6
	v_and_b32_e32 v8, 0xffff0000, v7
	v_or_b32_sdwa v7, v6, v0 dst_sel:DWORD dst_unused:UNUSED_PAD src0_sel:DWORD src1_sel:WORD_1
	v_or_b32_sdwa v6, v8, v5 dst_sel:DWORD dst_unused:UNUSED_PAD src0_sel:DWORD src1_sel:WORD_1
	v_and_b32_sdwa v8, v46, v242 dst_sel:DWORD dst_unused:UNUSED_PAD src0_sel:WORD_1 src1_sel:DWORD
	v_and_b32_sdwa v9, v48, v242 dst_sel:DWORD dst_unused:UNUSED_PAD src0_sel:WORD_1 src1_sel:DWORD
	v_and_b32_sdwa v0, v47, v242 dst_sel:DWORD dst_unused:UNUSED_PAD src0_sel:WORD_1 src1_sel:DWORD
	v_and_b32_sdwa v5, v49, v242 dst_sel:DWORD dst_unused:UNUSED_PAD src0_sel:WORD_1 src1_sel:DWORD
	v_add3_u32 v8, v46, v8, s71
	v_add3_u32 v9, v48, v9, s71
	v_add3_u32 v5, v49, v5, s71
	v_add3_u32 v0, v47, v0, s71
	v_and_b32_e32 v8, 0xffff0000, v8
	v_and_b32_e32 v10, 0xffff0000, v9
	v_or_b32_sdwa v9, v8, v0 dst_sel:DWORD dst_unused:UNUSED_PAD src0_sel:DWORD src1_sel:WORD_1
	v_or_b32_sdwa v8, v10, v5 dst_sel:DWORD dst_unused:UNUSED_PAD src0_sel:DWORD src1_sel:WORD_1
	global_store_dwordx4 v[12:13], v[6:9], off offset:512
	v_and_b32_sdwa v0, v43, v242 dst_sel:DWORD dst_unused:UNUSED_PAD src0_sel:WORD_1 src1_sel:DWORD
	v_and_b32_sdwa v5, v45, v242 dst_sel:DWORD dst_unused:UNUSED_PAD src0_sel:WORD_1 src1_sel:DWORD
	v_and_b32_sdwa v6, v42, v242 dst_sel:DWORD dst_unused:UNUSED_PAD src0_sel:WORD_1 src1_sel:DWORD
	v_and_b32_sdwa v7, v44, v242 dst_sel:DWORD dst_unused:UNUSED_PAD src0_sel:WORD_1 src1_sel:DWORD
	v_add3_u32 v6, v42, v6, s71
	v_add3_u32 v7, v44, v7, s71
	v_add3_u32 v5, v45, v5, s71
	v_add3_u32 v0, v43, v0, s71
; DI uint4 pack8(const float* f) { uint4 o; o.x = pk2(f[0], f[1]); o.y = pk2(f[2], f[3]); o.z = pk2(f[4], f[5]); o.w = pk2(f[6], f[7]); return o; }
; template <int D> DI void dn_out(float (&x)[64], lf_t Kl, lf_t Ql, lf_t Gn, bf16_t* DW, bf16_t* DQE, bf16_t* DKT, bf16_t* DUT, float* DEG, int item, int t) {
;     ...
;             if (t < 128) { bf16_t* uo = DUT + (((size_t)D * 1152 + item) * 128 + t) * 64;
; #pragma unroll
;                 for (int g8 = 0; g8 < 8; ++g8) *(uint4*)(uo + 8 * g8) = pack8(x + 8 * g8);
	v_and_b32_e32 v6, 0xffff0000, v6
	v_and_b32_e32 v8, 0xffff0000, v7
	v_or_b32_sdwa v7, v6, v0 dst_sel:DWORD dst_unused:UNUSED_PAD src0_sel:DWORD src1_sel:WORD_1
	v_or_b32_sdwa v6, v8, v5 dst_sel:DWORD dst_unused:UNUSED_PAD src0_sel:DWORD src1_sel:WORD_1
	v_and_b32_sdwa v8, v38, v242 dst_sel:DWORD dst_unused:UNUSED_PAD src0_sel:WORD_1 src1_sel:DWORD
	v_and_b32_sdwa v9, v40, v242 dst_sel:DWORD dst_unused:UNUSED_PAD src0_sel:WORD_1 src1_sel:DWORD
	v_and_b32_sdwa v0, v39, v242 dst_sel:DWORD dst_unused:UNUSED_PAD src0_sel:WORD_1 src1_sel:DWORD
	v_and_b32_sdwa v5, v41, v242 dst_sel:DWORD dst_unused:UNUSED_PAD src0_sel:WORD_1 src1_sel:DWORD
	v_add3_u32 v8, v38, v8, s71
	v_add3_u32 v9, v40, v9, s71
	v_add3_u32 v5, v41, v5, s71
	v_add3_u32 v0, v39, v0, s71
	v_and_b32_e32 v8, 0xffff0000, v8
	v_and_b32_e32 v10, 0xffff0000, v9
	v_or_b32_sdwa v9, v8, v0 dst_sel:DWORD dst_unused:UNUSED_PAD src0_sel:DWORD src1_sel:WORD_1
	v_or_b32_sdwa v8, v10, v5 dst_sel:DWORD dst_unused:UNUSED_PAD src0_sel:DWORD src1_sel:WORD_1
	global_store_dwordx4 v[12:13], v[6:9], off offset:768
	v_and_b32_sdwa v0, v35, v242 dst_sel:DWORD dst_unused:UNUSED_PAD src0_sel:WORD_1 src1_sel:DWORD
	v_and_b32_sdwa v5, v37, v242 dst_sel:DWORD dst_unused:UNUSED_PAD src0_sel:WORD_1 src1_sel:DWORD
	v_and_b32_sdwa v6, v34, v242 dst_sel:DWORD dst_unused:UNUSED_PAD src0_sel:WORD_1 src1_sel:DWORD
	v_and_b32_sdwa v7, v36, v242 dst_sel:DWORD dst_unused:UNUSED_PAD src0_sel:WORD_1 src1_sel:DWORD
	v_add3_u32 v6, v34, v6, s71
	v_add3_u32 v7, v36, v7, s71
	v_add3_u32 v5, v37, v5, s71
	v_add3_u32 v0, v35, v0, s71
	v_and_b32_e32 v6, 0xffff0000, v6
	v_and_b32_e32 v8, 0xffff0000, v7
	v_or_b32_sdwa v7, v6, v0 dst_sel:DWORD dst_unused:UNUSED_PAD src0_sel:DWORD src1_sel:WORD_1
	v_or_b32_sdwa v6, v8, v5 dst_sel:DWORD dst_unused:UNUSED_PAD src0_sel:DWORD src1_sel:WORD_1
	v_and_b32_sdwa v8, v30, v242 dst_sel:DWORD dst_unused:UNUSED_PAD src0_sel:WORD_1 src1_sel:DWORD
	v_and_b32_sdwa v9, v32, v242 dst_sel:DWORD dst_unused:UNUSED_PAD src0_sel:WORD_1 src1_sel:DWORD
	v_and_b32_sdwa v0, v31, v242 dst_sel:DWORD dst_unused:UNUSED_PAD src0_sel:WORD_1 src1_sel:DWORD
	v_and_b32_sdwa v5, v33, v242 dst_sel:DWORD dst_unused:UNUSED_PAD src0_sel:WORD_1 src1_sel:DWORD
	v_add3_u32 v8, v30, v8, s71
	v_add3_u32 v9, v32, v9, s71
	v_add3_u32 v5, v33, v5, s71
	v_add3_u32 v0, v31, v0, s71
	v_and_b32_e32 v8, 0xffff0000, v8
	v_and_b32_e32 v10, 0xffff0000, v9
	v_or_b32_sdwa v9, v8, v0 dst_sel:DWORD dst_unused:UNUSED_PAD src0_sel:DWORD src1_sel:WORD_1
	v_or_b32_sdwa v8, v10, v5 dst_sel:DWORD dst_unused:UNUSED_PAD src0_sel:DWORD src1_sel:WORD_1
	global_store_dwordx4 v[12:13], v[6:9], off offset:1024
	v_and_b32_sdwa v0, v27, v242 dst_sel:DWORD dst_unused:UNUSED_PAD src0_sel:WORD_1 src1_sel:DWORD
	v_and_b32_sdwa v5, v29, v242 dst_sel:DWORD dst_unused:UNUSED_PAD src0_sel:WORD_1 src1_sel:DWORD
	v_and_b32_sdwa v6, v26, v242 dst_sel:DWORD dst_unused:UNUSED_PAD src0_sel:WORD_1 src1_sel:DWORD
	v_and_b32_sdwa v7, v28, v242 dst_sel:DWORD dst_unused:UNUSED_PAD src0_sel:WORD_1 src1_sel:DWORD
	v_add3_u32 v6, v26, v6, s71
	v_add3_u32 v7, v28, v7, s71
	v_add3_u32 v5, v29, v5, s71
	v_add3_u32 v0, v27, v0, s71
	v_and_b32_e32 v6, 0xffff0000, v6
	v_and_b32_e32 v8, 0xffff0000, v7
	v_or_b32_sdwa v7, v6, v0 dst_sel:DWORD dst_unused:UNUSED_PAD src0_sel:DWORD src1_sel:WORD_1
	v_or_b32_sdwa v6, v8, v5 dst_sel:DWORD dst_unused:UNUSED_PAD src0_sel:DWORD src1_sel:WORD_1
	v_and_b32_sdwa v8, v22, v242 dst_sel:DWORD dst_unused:UNUSED_PAD src0_sel:WORD_1 src1_sel:DWORD
	v_and_b32_sdwa v9, v24, v242 dst_sel:DWORD dst_unused:UNUSED_PAD src0_sel:WORD_1 src1_sel:DWORD
	v_and_b32_sdwa v0, v23, v242 dst_sel:DWORD dst_unused:UNUSED_PAD src0_sel:WORD_1 src1_sel:DWORD
; DI uint4 pack8(const float* f) { uint4 o; o.x = pk2(f[0], f[1]); o.y = pk2(f[2], f[3]); o.z = pk2(f[4], f[5]); o.w = pk2(f[6], f[7]); return o; }
; template <int D> DI void dn_out(float (&x)[64], lf_t Kl, lf_t Ql, lf_t Gn, bf16_t* DW, bf16_t* DQE, bf16_t* DKT, bf16_t* DUT, float* DEG, int item, int t) {
;     ...
;             if (t < 128) { bf16_t* uo = DUT + (((size_t)D * 1152 + item) * 128 + t) * 64;
; #pragma unroll
;                 for (int g8 = 0; g8 < 8; ++g8) *(uint4*)(uo + 8 * g8) = pack8(x + 8 * g8);
	v_and_b32_sdwa v5, v25, v242 dst_sel:DWORD dst_unused:UNUSED_PAD src0_sel:WORD_1 src1_sel:DWORD
	v_add3_u32 v8, v22, v8, s71
	v_add3_u32 v9, v24, v9, s71
	v_add3_u32 v5, v25, v5, s71
	v_add3_u32 v0, v23, v0, s71
	v_and_b32_e32 v8, 0xffff0000, v8
	v_and_b32_e32 v10, 0xffff0000, v9
	v_or_b32_sdwa v9, v8, v0 dst_sel:DWORD dst_unused:UNUSED_PAD src0_sel:DWORD src1_sel:WORD_1
	v_or_b32_sdwa v8, v10, v5 dst_sel:DWORD dst_unused:UNUSED_PAD src0_sel:DWORD src1_sel:WORD_1
	global_store_dwordx4 v[12:13], v[6:9], off offset:1280
	v_and_b32_sdwa v0, v63, v242 dst_sel:DWORD dst_unused:UNUSED_PAD src0_sel:WORD_1 src1_sel:DWORD
	v_and_b32_sdwa v5, v65, v242 dst_sel:DWORD dst_unused:UNUSED_PAD src0_sel:WORD_1 src1_sel:DWORD
	v_and_b32_sdwa v6, v61, v242 dst_sel:DWORD dst_unused:UNUSED_PAD src0_sel:WORD_1 src1_sel:DWORD
	v_and_b32_sdwa v7, v64, v242 dst_sel:DWORD dst_unused:UNUSED_PAD src0_sel:WORD_1 src1_sel:DWORD
	v_add3_u32 v6, v61, v6, s71
	v_add3_u32 v7, v64, v7, s71
	v_add3_u32 v5, v65, v5, s71
	v_add3_u32 v0, v63, v0, s71
	v_and_b32_e32 v6, 0xffff0000, v6
	v_and_b32_e32 v8, 0xffff0000, v7
	v_or_b32_sdwa v7, v6, v0 dst_sel:DWORD dst_unused:UNUSED_PAD src0_sel:DWORD src1_sel:WORD_1
	v_or_b32_sdwa v6, v8, v5 dst_sel:DWORD dst_unused:UNUSED_PAD src0_sel:DWORD src1_sel:WORD_1
	v_and_b32_sdwa v8, v11, v242 dst_sel:DWORD dst_unused:UNUSED_PAD src0_sel:WORD_1 src1_sel:DWORD
	v_and_b32_sdwa v9, v75, v242 dst_sel:DWORD dst_unused:UNUSED_PAD src0_sel:WORD_1 src1_sel:DWORD
	v_and_b32_sdwa v0, v74, v242 dst_sel:DWORD dst_unused:UNUSED_PAD src0_sel:WORD_1 src1_sel:DWORD
	v_and_b32_sdwa v5, v76, v242 dst_sel:DWORD dst_unused:UNUSED_PAD src0_sel:WORD_1 src1_sel:DWORD
	v_add3_u32 v8, v11, v8, s71
	v_add3_u32 v9, v75, v9, s71
	v_add3_u32 v5, v76, v5, s71
	v_add3_u32 v0, v74, v0, s71
	v_and_b32_e32 v8, 0xffff0000, v8
	v_and_b32_e32 v10, 0xffff0000, v9
	v_or_b32_sdwa v9, v8, v0 dst_sel:DWORD dst_unused:UNUSED_PAD src0_sel:DWORD src1_sel:WORD_1
	v_or_b32_sdwa v8, v10, v5 dst_sel:DWORD dst_unused:UNUSED_PAD src0_sel:DWORD src1_sel:WORD_1
	global_store_dwordx4 v[12:13], v[6:9], off offset:1536
	v_and_b32_sdwa v0, v78, v242 dst_sel:DWORD dst_unused:UNUSED_PAD src0_sel:WORD_1 src1_sel:DWORD
	v_and_b32_sdwa v5, v80, v242 dst_sel:DWORD dst_unused:UNUSED_PAD src0_sel:WORD_1 src1_sel:DWORD
	v_and_b32_sdwa v6, v77, v242 dst_sel:DWORD dst_unused:UNUSED_PAD src0_sel:WORD_1 src1_sel:DWORD
	v_and_b32_sdwa v7, v79, v242 dst_sel:DWORD dst_unused:UNUSED_PAD src0_sel:WORD_1 src1_sel:DWORD
	v_add3_u32 v6, v77, v6, s71
	v_add3_u32 v7, v79, v7, s71
	v_add3_u32 v5, v80, v5, s71
	v_add3_u32 v0, v78, v0, s71
	v_and_b32_e32 v6, 0xffff0000, v6
	v_and_b32_e32 v8, 0xffff0000, v7
	v_or_b32_sdwa v7, v6, v0 dst_sel:DWORD dst_unused:UNUSED_PAD src0_sel:DWORD src1_sel:WORD_1
	v_or_b32_sdwa v6, v8, v5 dst_sel:DWORD dst_unused:UNUSED_PAD src0_sel:DWORD src1_sel:WORD_1
	v_and_b32_sdwa v8, v68, v242 dst_sel:DWORD dst_unused:UNUSED_PAD src0_sel:WORD_1 src1_sel:DWORD
	v_and_b32_sdwa v9, v81, v242 dst_sel:DWORD dst_unused:UNUSED_PAD src0_sel:WORD_1 src1_sel:DWORD
	v_and_b32_sdwa v0, v69, v242 dst_sel:DWORD dst_unused:UNUSED_PAD src0_sel:WORD_1 src1_sel:DWORD
	v_and_b32_sdwa v5, v82, v242 dst_sel:DWORD dst_unused:UNUSED_PAD src0_sel:WORD_1 src1_sel:DWORD
	v_add3_u32 v8, v68, v8, s71
	v_add3_u32 v9, v81, v9, s71
	v_add3_u32 v5, v82, v5, s71
	v_add3_u32 v0, v69, v0, s71
	v_and_b32_e32 v8, 0xffff0000, v8
	v_and_b32_e32 v10, 0xffff0000, v9
	v_or_b32_sdwa v9, v8, v0 dst_sel:DWORD dst_unused:UNUSED_PAD src0_sel:DWORD src1_sel:WORD_1
	v_or_b32_sdwa v8, v10, v5 dst_sel:DWORD dst_unused:UNUSED_PAD src0_sel:DWORD src1_sel:WORD_1
	global_store_dwordx4 v[12:13], v[6:9], off offset:1792
	s_nop 1
	v_mov_b64_e32 v[8:9], s[20:21]

; DI uint4 pack8(const float* f) { uint4 o; o.x = pk2(f[0], f[1]); o.y = pk2(f[2], f[3]); o.z = pk2(f[4], f[5]); o.w = pk2(f[6], f[7]); return o; }
; template <int D> DI void dn_out(float (&x)[64], lf_t Kl, lf_t Ql, lf_t Gn, bf16_t* DW, bf16_t* DQE, bf16_t* DKT, bf16_t* DUT, float* DEG, int item, int t) {
;     ...
;             if (t < 128) { bf16_t* uo = DUT + (((size_t)D * 1152 + item) * 128 + t) * 64;
; #pragma unroll
;                 for (int g8 = 0; g8 < 8; ++g8) *(uint4*)(uo + 8 * g8) = pack8(x + 8 * g8);
.LBB0_665:
	s_andn2_saveexec_b64 s[20:21], s[20:21]
	s_cbranch_execz .LBB0_667
	v_ashrrev_i32_e32 v5, 31, v4
	v_and_b32_e32 v6, 15, v4
	v_lshrrev_b32_e32 v7, 4, v4
	v_lshlrev_b32_e32 v6, 4, v6
	v_lshl_add_u32 v6, v7, 11, v6
	v_mov_b32_e32 v7, 0
	s_add_u32 s28, s66, s12
	v_and_b32_sdwa v5, v2, v242 dst_sel:DWORD dst_unused:UNUSED_PAD src0_sel:WORD_1 src1_sel:DWORD
	s_addc_u32 s29, s67, s13
	v_add3_u32 v2, v2, v5, s71
	v_and_b32_sdwa v5, v70, v242 dst_sel:DWORD dst_unused:UNUSED_PAD src0_sel:WORD_1 src1_sel:DWORD
	v_lshl_add_u64 v[12:13], s[28:29], 0, v[6:7]
	v_and_b32_sdwa v0, v72, v242 dst_sel:DWORD dst_unused:UNUSED_PAD src0_sel:WORD_1 src1_sel:DWORD
	v_and_b32_sdwa v6, v73, v242 dst_sel:DWORD dst_unused:UNUSED_PAD src0_sel:WORD_1 src1_sel:DWORD
	v_add3_u32 v5, v70, v5, s71
	v_add3_u32 v0, v72, v0, s71
	v_add3_u32 v6, v73, v6, s71
	v_and_b32_e32 v5, 0xffff0000, v5
	v_and_b32_e32 v6, 0xffff0000, v6
	v_or_b32_sdwa v7, v5, v0 dst_sel:DWORD dst_unused:UNUSED_PAD src0_sel:DWORD src1_sel:WORD_1
	v_and_b32_sdwa v5, v56, v242 dst_sel:DWORD dst_unused:UNUSED_PAD src0_sel:WORD_1 src1_sel:DWORD
	v_and_b32_sdwa v8, v67, v242 dst_sel:DWORD dst_unused:UNUSED_PAD src0_sel:WORD_1 src1_sel:DWORD
	v_or_b32_sdwa v6, v6, v2 dst_sel:DWORD dst_unused:UNUSED_PAD src0_sel:DWORD src1_sel:WORD_1
	v_and_b32_sdwa v0, v66, v242 dst_sel:DWORD dst_unused:UNUSED_PAD src0_sel:WORD_1 src1_sel:DWORD
	v_and_b32_sdwa v2, v71, v242 dst_sel:DWORD dst_unused:UNUSED_PAD src0_sel:WORD_1 src1_sel:DWORD
	v_add3_u32 v5, v56, v5, s71
	v_add3_u32 v8, v67, v8, s71
	s_mov_b32 s4, 0x2766a000
	v_add3_u32 v2, v71, v2, s71
	v_add3_u32 v0, v66, v0, s71
	v_and_b32_e32 v5, 0xffff0000, v5
	v_and_b32_e32 v8, 0xffff0000, v8
	v_add_co_u32_e32 v12, vcc, s4, v12
	v_or_b32_sdwa v9, v5, v0 dst_sel:DWORD dst_unused:UNUSED_PAD src0_sel:DWORD src1_sel:WORD_1
	v_or_b32_sdwa v8, v8, v2 dst_sel:DWORD dst_unused:UNUSED_PAD src0_sel:DWORD src1_sel:WORD_1
	v_addc_co_u32_e32 v13, vcc, 0, v13, vcc
	global_store_dwordx4 v[12:13], v[6:9], off
	v_and_b32_sdwa v5, v3, v242 dst_sel:DWORD dst_unused:UNUSED_PAD src0_sel:WORD_1 src1_sel:DWORD
	v_and_b32_sdwa v0, v51, v242 dst_sel:DWORD dst_unused:UNUSED_PAD src0_sel:WORD_1 src1_sel:DWORD
	v_and_b32_sdwa v6, v57, v242 dst_sel:DWORD dst_unused:UNUSED_PAD src0_sel:WORD_1 src1_sel:DWORD
	v_and_b32_sdwa v2, v62, v242 dst_sel:DWORD dst_unused:UNUSED_PAD src0_sel:WORD_1 src1_sel:DWORD
	v_add3_u32 v3, v3, v5, s71
	v_add3_u32 v5, v57, v6, s71
	v_add3_u32 v2, v62, v2, s71
	v_add3_u32 v0, v51, v0, s71
	v_and_b32_e32 v3, 0xffff0000, v3
	v_and_b32_e32 v5, 0xffff0000, v5
	v_or_b32_sdwa v7, v3, v0 dst_sel:DWORD dst_unused:UNUSED_PAD src0_sel:DWORD src1_sel:WORD_1
	v_or_b32_sdwa v6, v5, v2 dst_sel:DWORD dst_unused:UNUSED_PAD src0_sel:DWORD src1_sel:WORD_1
	v_and_b32_sdwa v3, v50, v242 dst_sel:DWORD dst_unused:UNUSED_PAD src0_sel:WORD_1 src1_sel:DWORD
	v_and_b32_sdwa v5, v59, v242 dst_sel:DWORD dst_unused:UNUSED_PAD src0_sel:WORD_1 src1_sel:DWORD
	v_and_b32_sdwa v0, v58, v242 dst_sel:DWORD dst_unused:UNUSED_PAD src0_sel:WORD_1 src1_sel:DWORD
	v_and_b32_sdwa v2, v60, v242 dst_sel:DWORD dst_unused:UNUSED_PAD src0_sel:WORD_1 src1_sel:DWORD
	v_add3_u32 v3, v50, v3, s71
	v_add3_u32 v5, v59, v5, s71
	v_add3_u32 v2, v60, v2, s71
	v_add3_u32 v0, v58, v0, s71
	v_and_b32_e32 v3, 0xffff0000, v3
	v_and_b32_e32 v5, 0xffff0000, v5
	v_or_b32_sdwa v9, v3, v0 dst_sel:DWORD dst_unused:UNUSED_PAD src0_sel:DWORD src1_sel:WORD_1
	v_or_b32_sdwa v8, v5, v2 dst_sel:DWORD dst_unused:UNUSED_PAD src0_sel:DWORD src1_sel:WORD_1
	v_and_b32_sdwa v3, v52, v242 dst_sel:DWORD dst_unused:UNUSED_PAD src0_sel:WORD_1 src1_sel:DWORD
	v_and_b32_sdwa v5, v54, v242 dst_sel:DWORD dst_unused:UNUSED_PAD src0_sel:WORD_1 src1_sel:DWORD
	v_and_b32_sdwa v0, v53, v242 dst_sel:DWORD dst_unused:UNUSED_PAD src0_sel:WORD_1 src1_sel:DWORD
	v_and_b32_sdwa v2, v55, v242 dst_sel:DWORD dst_unused:UNUSED_PAD src0_sel:WORD_1 src1_sel:DWORD
	v_add3_u32 v3, v52, v3, s71
	v_add3_u32 v5, v54, v5, s71
	v_add3_u32 v2, v55, v2, s71
	v_add3_u32 v0, v53, v0, s71
	v_and_b32_e32 v3, 0xffff0000, v3
	v_and_b32_e32 v5, 0xffff0000, v5
	global_store_dwordx4 v[12:13], v[6:9], off offset:256
	s_nop 1
	v_or_b32_sdwa v7, v3, v0 dst_sel:DWORD dst_unused:UNUSED_PAD src0_sel:DWORD src1_sel:WORD_1
	v_or_b32_sdwa v6, v5, v2 dst_sel:DWORD dst_unused:UNUSED_PAD src0_sel:DWORD src1_sel:WORD_1
	v_and_b32_sdwa v3, v46, v242 dst_sel:DWORD dst_unused:UNUSED_PAD src0_sel:WORD_1 src1_sel:DWORD
	v_and_b32_sdwa v5, v48, v242 dst_sel:DWORD dst_unused:UNUSED_PAD src0_sel:WORD_1 src1_sel:DWORD
	v_and_b32_sdwa v0, v47, v242 dst_sel:DWORD dst_unused:UNUSED_PAD src0_sel:WORD_1 src1_sel:DWORD
	v_and_b32_sdwa v2, v49, v242 dst_sel:DWORD dst_unused:UNUSED_PAD src0_sel:WORD_1 src1_sel:DWORD
	v_add3_u32 v3, v46, v3, s71
	v_add3_u32 v5, v48, v5, s71
	v_add3_u32 v2, v49, v2, s71
	v_add3_u32 v0, v47, v0, s71
	v_and_b32_e32 v3, 0xffff0000, v3
	v_and_b32_e32 v5, 0xffff0000, v5
	v_or_b32_sdwa v9, v3, v0 dst_sel:DWORD dst_unused:UNUSED_PAD src0_sel:DWORD src1_sel:WORD_1
	v_or_b32_sdwa v8, v5, v2 dst_sel:DWORD dst_unused:UNUSED_PAD src0_sel:DWORD src1_sel:WORD_1
	v_and_b32_sdwa v3, v42, v242 dst_sel:DWORD dst_unused:UNUSED_PAD src0_sel:WORD_1 src1_sel:DWORD
	v_and_b32_sdwa v5, v44, v242 dst_sel:DWORD dst_unused:UNUSED_PAD src0_sel:WORD_1 src1_sel:DWORD
	v_and_b32_sdwa v0, v43, v242 dst_sel:DWORD dst_unused:UNUSED_PAD src0_sel:WORD_1 src1_sel:DWORD
	v_and_b32_sdwa v2, v45, v242 dst_sel:DWORD dst_unused:UNUSED_PAD src0_sel:WORD_1 src1_sel:DWORD
	v_add3_u32 v3, v42, v3, s71
	v_add3_u32 v5, v44, v5, s71
	v_add3_u32 v2, v45, v2, s71
	v_add3_u32 v0, v43, v0, s71
	v_and_b32_e32 v3, 0xffff0000, v3
; DI uint4 pack8(const float* f) { uint4 o; o.x = pk2(f[0], f[1]); o.y = pk2(f[2], f[3]); o.z = pk2(f[4], f[5]); o.w = pk2(f[6], f[7]); return o; }
; template <int D> DI void dn_out(float (&x)[64], lf_t Kl, lf_t Ql, lf_t Gn, bf16_t* DW, bf16_t* DQE, bf16_t* DKT, bf16_t* DUT, float* DEG, int item, int t) {
;     ...
;             if (t < 128) { bf16_t* uo = DUT + (((size_t)D * 1152 + item) * 128 + t) * 64;
; #pragma unroll
;                 for (int g8 = 0; g8 < 8; ++g8) *(uint4*)(uo + 8 * g8) = pack8(x + 8 * g8);
	v_and_b32_e32 v5, 0xffff0000, v5
	global_store_dwordx4 v[12:13], v[6:9], off offset:512
	s_nop 1
	v_or_b32_sdwa v7, v3, v0 dst_sel:DWORD dst_unused:UNUSED_PAD src0_sel:DWORD src1_sel:WORD_1
	v_or_b32_sdwa v6, v5, v2 dst_sel:DWORD dst_unused:UNUSED_PAD src0_sel:DWORD src1_sel:WORD_1
	v_and_b32_sdwa v3, v38, v242 dst_sel:DWORD dst_unused:UNUSED_PAD src0_sel:WORD_1 src1_sel:DWORD
	v_and_b32_sdwa v5, v40, v242 dst_sel:DWORD dst_unused:UNUSED_PAD src0_sel:WORD_1 src1_sel:DWORD
	v_and_b32_sdwa v0, v39, v242 dst_sel:DWORD dst_unused:UNUSED_PAD src0_sel:WORD_1 src1_sel:DWORD
	v_and_b32_sdwa v2, v41, v242 dst_sel:DWORD dst_unused:UNUSED_PAD src0_sel:WORD_1 src1_sel:DWORD
	v_add3_u32 v3, v38, v3, s71
	v_add3_u32 v5, v40, v5, s71
	v_add3_u32 v2, v41, v2, s71
	v_add3_u32 v0, v39, v0, s71
	v_and_b32_e32 v3, 0xffff0000, v3
	v_and_b32_e32 v5, 0xffff0000, v5
	v_or_b32_sdwa v9, v3, v0 dst_sel:DWORD dst_unused:UNUSED_PAD src0_sel:DWORD src1_sel:WORD_1
	v_or_b32_sdwa v8, v5, v2 dst_sel:DWORD dst_unused:UNUSED_PAD src0_sel:DWORD src1_sel:WORD_1
	v_and_b32_sdwa v3, v34, v242 dst_sel:DWORD dst_unused:UNUSED_PAD src0_sel:WORD_1 src1_sel:DWORD
	v_and_b32_sdwa v5, v36, v242 dst_sel:DWORD dst_unused:UNUSED_PAD src0_sel:WORD_1 src1_sel:DWORD
	v_and_b32_sdwa v0, v35, v242 dst_sel:DWORD dst_unused:UNUSED_PAD src0_sel:WORD_1 src1_sel:DWORD
	v_and_b32_sdwa v2, v37, v242 dst_sel:DWORD dst_unused:UNUSED_PAD src0_sel:WORD_1 src1_sel:DWORD
	v_add3_u32 v3, v34, v3, s71
	v_add3_u32 v5, v36, v5, s71
	v_add3_u32 v2, v37, v2, s71
	v_add3_u32 v0, v35, v0, s71
	v_and_b32_e32 v3, 0xffff0000, v3
	v_and_b32_e32 v5, 0xffff0000, v5
	global_store_dwordx4 v[12:13], v[6:9], off offset:768
	s_nop 1
	v_or_b32_sdwa v7, v3, v0 dst_sel:DWORD dst_unused:UNUSED_PAD src0_sel:DWORD src1_sel:WORD_1
	v_or_b32_sdwa v6, v5, v2 dst_sel:DWORD dst_unused:UNUSED_PAD src0_sel:DWORD src1_sel:WORD_1
	v_and_b32_sdwa v3, v30, v242 dst_sel:DWORD dst_unused:UNUSED_PAD src0_sel:WORD_1 src1_sel:DWORD
	v_and_b32_sdwa v5, v32, v242 dst_sel:DWORD dst_unused:UNUSED_PAD src0_sel:WORD_1 src1_sel:DWORD
	v_and_b32_sdwa v0, v31, v242 dst_sel:DWORD dst_unused:UNUSED_PAD src0_sel:WORD_1 src1_sel:DWORD
	v_and_b32_sdwa v2, v33, v242 dst_sel:DWORD dst_unused:UNUSED_PAD src0_sel:WORD_1 src1_sel:DWORD
	v_add3_u32 v3, v30, v3, s71
	v_add3_u32 v5, v32, v5, s71
	v_add3_u32 v2, v33, v2, s71
	v_add3_u32 v0, v31, v0, s71
	v_and_b32_e32 v3, 0xffff0000, v3
	v_and_b32_e32 v5, 0xffff0000, v5
	v_or_b32_sdwa v9, v3, v0 dst_sel:DWORD dst_unused:UNUSED_PAD src0_sel:DWORD src1_sel:WORD_1
	v_or_b32_sdwa v8, v5, v2 dst_sel:DWORD dst_unused:UNUSED_PAD src0_sel:DWORD src1_sel:WORD_1
	v_and_b32_sdwa v3, v26, v242 dst_sel:DWORD dst_unused:UNUSED_PAD src0_sel:WORD_1 src1_sel:DWORD
	v_and_b32_sdwa v5, v28, v242 dst_sel:DWORD dst_unused:UNUSED_PAD src0_sel:WORD_1 src1_sel:DWORD
	v_and_b32_sdwa v0, v27, v242 dst_sel:DWORD dst_unused:UNUSED_PAD src0_sel:WORD_1 src1_sel:DWORD
	v_and_b32_sdwa v2, v29, v242 dst_sel:DWORD dst_unused:UNUSED_PAD src0_sel:WORD_1 src1_sel:DWORD
	v_add3_u32 v3, v26, v3, s71
	v_add3_u32 v5, v28, v5, s71
	v_add3_u32 v2, v29, v2, s71
	v_add3_u32 v0, v27, v0, s71
	v_and_b32_e32 v3, 0xffff0000, v3
	v_and_b32_e32 v5, 0xffff0000, v5
	global_store_dwordx4 v[12:13], v[6:9], off offset:1024
	s_nop 1
	v_or_b32_sdwa v7, v3, v0 dst_sel:DWORD dst_unused:UNUSED_PAD src0_sel:DWORD src1_sel:WORD_1
	v_or_b32_sdwa v6, v5, v2 dst_sel:DWORD dst_unused:UNUSED_PAD src0_sel:DWORD src1_sel:WORD_1
	v_and_b32_sdwa v3, v22, v242 dst_sel:DWORD dst_unused:UNUSED_PAD src0_sel:WORD_1 src1_sel:DWORD
	v_and_b32_sdwa v5, v24, v242 dst_sel:DWORD dst_unused:UNUSED_PAD src0_sel:WORD_1 src1_sel:DWORD
	v_and_b32_sdwa v0, v23, v242 dst_sel:DWORD dst_unused:UNUSED_PAD src0_sel:WORD_1 src1_sel:DWORD
; DI uint4 pack8(const float* f) { uint4 o; o.x = pk2(f[0], f[1]); o.y = pk2(f[2], f[3]); o.z = pk2(f[4], f[5]); o.w = pk2(f[6], f[7]); return o; }
; template <int D> DI void dn_out(float (&x)[64], lf_t Kl, lf_t Ql, lf_t Gn, bf16_t* DW, bf16_t* DQE, bf16_t* DKT, bf16_t* DUT, float* DEG, int item, int t) {
;     ...
;             if (t < 128) { bf16_t* uo = DUT + (((size_t)D * 1152 + item) * 128 + t) * 64;
; #pragma unroll
;                 for (int g8 = 0; g8 < 8; ++g8) *(uint4*)(uo + 8 * g8) = pack8(x + 8 * g8);
	v_and_b32_sdwa v2, v25, v242 dst_sel:DWORD dst_unused:UNUSED_PAD src0_sel:WORD_1 src1_sel:DWORD
	v_add3_u32 v3, v22, v3, s71
	v_add3_u32 v5, v24, v5, s71
	v_add3_u32 v2, v25, v2, s71
	v_add3_u32 v0, v23, v0, s71
	v_and_b32_e32 v3, 0xffff0000, v3
	v_and_b32_e32 v5, 0xffff0000, v5
	v_or_b32_sdwa v9, v3, v0 dst_sel:DWORD dst_unused:UNUSED_PAD src0_sel:DWORD src1_sel:WORD_1
	v_or_b32_sdwa v8, v5, v2 dst_sel:DWORD dst_unused:UNUSED_PAD src0_sel:DWORD src1_sel:WORD_1
	v_and_b32_sdwa v3, v61, v242 dst_sel:DWORD dst_unused:UNUSED_PAD src0_sel:WORD_1 src1_sel:DWORD
	v_and_b32_sdwa v5, v64, v242 dst_sel:DWORD dst_unused:UNUSED_PAD src0_sel:WORD_1 src1_sel:DWORD
	v_and_b32_sdwa v0, v63, v242 dst_sel:DWORD dst_unused:UNUSED_PAD src0_sel:WORD_1 src1_sel:DWORD
	v_and_b32_sdwa v2, v65, v242 dst_sel:DWORD dst_unused:UNUSED_PAD src0_sel:WORD_1 src1_sel:DWORD
	v_add3_u32 v3, v61, v3, s71
	v_add3_u32 v5, v64, v5, s71
	v_add3_u32 v2, v65, v2, s71
	v_add3_u32 v0, v63, v0, s71
	v_and_b32_e32 v3, 0xffff0000, v3
	v_and_b32_e32 v5, 0xffff0000, v5
	global_store_dwordx4 v[12:13], v[6:9], off offset:1280
	s_nop 1
	v_or_b32_sdwa v7, v3, v0 dst_sel:DWORD dst_unused:UNUSED_PAD src0_sel:DWORD src1_sel:WORD_1
	v_or_b32_sdwa v6, v5, v2 dst_sel:DWORD dst_unused:UNUSED_PAD src0_sel:DWORD src1_sel:WORD_1
	v_and_b32_sdwa v3, v11, v242 dst_sel:DWORD dst_unused:UNUSED_PAD src0_sel:WORD_1 src1_sel:DWORD
	v_and_b32_sdwa v5, v75, v242 dst_sel:DWORD dst_unused:UNUSED_PAD src0_sel:WORD_1 src1_sel:DWORD
	v_and_b32_sdwa v0, v74, v242 dst_sel:DWORD dst_unused:UNUSED_PAD src0_sel:WORD_1 src1_sel:DWORD
	v_and_b32_sdwa v2, v76, v242 dst_sel:DWORD dst_unused:UNUSED_PAD src0_sel:WORD_1 src1_sel:DWORD
	v_add3_u32 v3, v11, v3, s71
	v_add3_u32 v5, v75, v5, s71
	v_add3_u32 v2, v76, v2, s71
	v_add3_u32 v0, v74, v0, s71
	v_and_b32_e32 v3, 0xffff0000, v3
	v_and_b32_e32 v5, 0xffff0000, v5
	v_or_b32_sdwa v9, v3, v0 dst_sel:DWORD dst_unused:UNUSED_PAD src0_sel:DWORD src1_sel:WORD_1
	v_or_b32_sdwa v8, v5, v2 dst_sel:DWORD dst_unused:UNUSED_PAD src0_sel:DWORD src1_sel:WORD_1
	v_and_b32_sdwa v3, v77, v242 dst_sel:DWORD dst_unused:UNUSED_PAD src0_sel:WORD_1 src1_sel:DWORD
	v_and_b32_sdwa v5, v79, v242 dst_sel:DWORD dst_unused:UNUSED_PAD src0_sel:WORD_1 src1_sel:DWORD
	v_and_b32_sdwa v0, v78, v242 dst_sel:DWORD dst_unused:UNUSED_PAD src0_sel:WORD_1 src1_sel:DWORD
	v_and_b32_sdwa v2, v80, v242 dst_sel:DWORD dst_unused:UNUSED_PAD src0_sel:WORD_1 src1_sel:DWORD
	v_add3_u32 v3, v77, v3, s71
	v_add3_u32 v5, v79, v5, s71
	v_add3_u32 v2, v80, v2, s71
	v_add3_u32 v0, v78, v0, s71
	v_and_b32_e32 v3, 0xffff0000, v3
	v_and_b32_e32 v5, 0xffff0000, v5
	global_store_dwordx4 v[12:13], v[6:9], off offset:1536
	s_nop 1
	v_or_b32_sdwa v7, v3, v0 dst_sel:DWORD dst_unused:UNUSED_PAD src0_sel:DWORD src1_sel:WORD_1
	v_or_b32_sdwa v6, v5, v2 dst_sel:DWORD dst_unused:UNUSED_PAD src0_sel:DWORD src1_sel:WORD_1
	v_and_b32_sdwa v3, v68, v242 dst_sel:DWORD dst_unused:UNUSED_PAD src0_sel:WORD_1 src1_sel:DWORD
	v_and_b32_sdwa v5, v81, v242 dst_sel:DWORD dst_unused:UNUSED_PAD src0_sel:WORD_1 src1_sel:DWORD
	v_and_b32_sdwa v0, v69, v242 dst_sel:DWORD dst_unused:UNUSED_PAD src0_sel:WORD_1 src1_sel:DWORD
	v_and_b32_sdwa v2, v82, v242 dst_sel:DWORD dst_unused:UNUSED_PAD src0_sel:WORD_1 src1_sel:DWORD
	v_add3_u32 v3, v68, v3, s71
	v_add3_u32 v5, v81, v5, s71
	v_add3_u32 v2, v82, v2, s71
	v_add3_u32 v0, v69, v0, s71
	v_and_b32_e32 v3, 0xffff0000, v3
	v_and_b32_e32 v5, 0xffff0000, v5
	v_or_b32_sdwa v9, v3, v0 dst_sel:DWORD dst_unused:UNUSED_PAD src0_sel:DWORD src1_sel:WORD_1
	v_or_b32_sdwa v8, v5, v2 dst_sel:DWORD dst_unused:UNUSED_PAD src0_sel:DWORD src1_sel:WORD_1
	global_store_dwordx4 v[12:13], v[6:9], off offset:1792
